# MLA fast path: the first S0 MFMA (with its fragment read and six deferred adds) is issued before the even-tile K/V LDS-DMA block instead of after it
# baseline (speedup 1.0000x reference)
.Lmla_fast_havek:
	s_mov_b32 s42, 0
	s_waitcnt lgkmcnt(0)
	v_mfma_f32_32x32x16_bf16 v[50:65], v[194:197], v[74:77], v[234:249]
	ds_read_b128 v[194:197], v0 offset:6656
	v_add_f32_e32 v254, v202, v203
	v_add_f32_e32 v255, v204, v205
	v_add_f32_e32 v254, v254, v206
	v_add_f32_e32 v255, v255, v207
	v_add_f32_e32 v254, v254, v208
	v_add_f32_e32 v255, v255, v209
	s_andn2_b64 vcc, exec, s[38:39]
	s_cbranch_vccnz .Lmla_fast_nodma
	s_add_i32 s34, s30, 2
	s_cmp_gt_u32 s34, s14
	s_cbranch_scc1 .Lmla_fast_d2
	s_and_b32 s8, s34, 2
	s_mulk_i32 s8, 0x6400
	s_add_i32 s34, s8, 0
	s_add_i32 s8, s34, s5
	s_mov_b32 m0, s8
	s_and_b64 vcc, exec, s[36:37]
	global_load_lds_dwordx4 v66, s[26:27]
	s_add_i32 m0, s8, 0x2000
	v_add_u32_e32 v66, v66, v134
	global_load_lds_dwordx4 v68, s[26:27]
	s_add_i32 m0, s8, 0x4000
	v_add_u32_e32 v68, v68, v136
	global_load_lds_dwordx4 v70, s[26:27]
	v_add_u32_e32 v70, v70, v138
	s_cbranch_vccnz .Lmla_fast_d2
	s_add_i32 m0, s34, 0x6000
	s_nop 0
	global_load_lds_dwordx4 v72, s[26:27]
	v_add_u32_e32 v72, v72, v140

.Lmla_fast_nodma:
	v_mfma_f32_32x32x16_bf16 v[50:65], v[150:153], v[78:81], v[50:65]
	ds_read_b128 v[150:153], v0 offset:6688
	v_add_f32_e32 v254, v254, v210
	v_add_f32_e32 v255, v255, v211
	v_add_f32_e32 v254, v254, v212
	v_add_f32_e32 v255, v255, v213
	v_add_f32_e32 v254, v254, v214
	v_add_f32_e32 v255, v255, v215
	v_mfma_f32_32x32x16_bf16 v[50:65], v[158:161], v[82:85], v[50:65]
	ds_read_b128 v[158:161], v0 offset:6720
	v_add_f32_e32 v254, v254, v216
	v_add_f32_e32 v255, v255, v217
	v_add_f32_e32 v254, v254, v218
	v_add_f32_e32 v255, v255, v219
	v_add_f32_e32 v254, v254, v220
	v_mfma_f32_32x32x16_bf16 v[50:65], v[162:165], v[86:89], v[50:65]
	ds_read_b128 v[162:165], v0 offset:6752
	v_add_f32_e32 v255, v255, v221
	v_add_f32_e32 v254, v254, v222
	v_add_f32_e32 v255, v255, v223
	v_add_f32_e32 v254, v254, v224
	v_add_f32_e32 v255, v255, v225
	v_mfma_f32_32x32x16_bf16 v[50:65], v[174:177], v[90:93], v[50:65]
	ds_read_b128 v[174:177], v0 offset:6784
	v_add_f32_e32 v254, v254, v226
	v_add_f32_e32 v255, v255, v227
	v_add_f32_e32 v254, v254, v228
	v_add_f32_e32 v255, v255, v229
	v_add_f32_e32 v254, v254, v230
	v_mfma_f32_32x32x16_bf16 v[50:65], v[178:181], v[94:97], v[50:65]
	ds_read_b128 v[178:181], v0 offset:6816
	v_add_f32_e32 v255, v255, v231
	v_add_f32_e32 v254, v254, v232
	v_add_f32_e32 v255, v255, v233
	v_add_f32_e32 v254, v254, v255
	v_add_f32_e32 v147, v147, v254
	s_waitcnt lgkmcnt(5)
	v_mfma_f32_32x32x16_bf16 v[34:49], v[194:197], v[74:77], v[234:249]
	ds_read_b64_tr_b16 v[126:127], v142 offset:13312
	ds_read_b64_tr_b16 v[128:129], v142 offset:14848
	ds_read_b64_tr_b16 v[124:125], v142 offset:14912
	ds_read_b64_tr_b16 v[122:123], v142 offset:13376
	s_waitcnt lgkmcnt(8)
	v_mfma_f32_32x32x16_bf16 v[34:49], v[150:153], v[78:81], v[34:49]
	ds_read_b64_tr_b16 v[118:119], v142 offset:16384
	ds_read_b64_tr_b16 v[120:121], v142 offset:17920
	ds_read_b64_tr_b16 v[116:117], v142 offset:17984
	ds_read_b64_tr_b16 v[114:115], v142 offset:16448
	s_waitcnt lgkmcnt(11)
	v_mfma_f32_32x32x16_bf16 v[34:49], v[158:161], v[82:85], v[34:49]
	ds_read_b64_tr_b16 v[110:111], v142 offset:19456
	ds_read_b64_tr_b16 v[112:113], v142 offset:20992
	ds_read_b64_tr_b16 v[108:109], v142 offset:21056
	ds_read_b64_tr_b16 v[106:107], v142 offset:19520
	s_waitcnt lgkmcnt(11)
	v_mfma_f32_32x32x16_bf16 v[34:49], v[162:165], v[86:89], v[34:49]
	ds_read_b64_tr_b16 v[102:103], v142 offset:22528
	ds_read_b64_tr_b16 v[104:105], v142 offset:24064
	ds_read_b64_tr_b16 v[100:101], v142 offset:24128
	ds_read_b64_tr_b16 v[98:99], v142 offset:22592
	v_mfma_f32_32x32x16_bf16 v[34:49], v[174:177], v[90:93], v[34:49]
	v_exp_f32_e32 v202, v50
	v_mfma_f32_32x32x16_bf16 v[34:49], v[178:181], v[94:97], v[34:49]
	s_and_b64 vcc, exec, s[16:17]
	s_cbranch_vccz .Lmla_fast_nostag
	s_waitcnt vmcnt(0) lgkmcnt(0)
	s_barrier
	s_mov_b64 s[16:17], 0
